# GL item P3 read batching, scan A state-update read batching, GL constant tables staged once per workgroup for consecutive GL items
# speedup vs baseline: 1.0321x; 1.0064x over previous
; #define LAS __attribute__((address_space(3)))
;     __device__ __forceinline__ const float* in(int i) const { return (const float*)(const __attribute__((address_space(1))) float*)ld(i); }
; __device__ __forceinline__ void lds_barrier() { asm volatile("s_waitcnt lgkmcnt(0)" ::: "memory"); __builtin_amdgcn_s_barrier(); asm volatile("" ::: "memory"); }
; __device__ __forceinline__ void gl_item_C(const Params& p, int l, int seg, int h, LAS float* sm, int tid, int lane, int wave) {
;     ...
;     lds_barrier();
;     {
;         const float* cw = p.in(25) + (size_t)l * 4 * 768;
;         for (int i = tid; i < 768; i += 512) { const int r = i / 48, c = i % 48; sm[L_GUP + i] = p.in(26)[(size_t)l * 16 * 192 + r * 192 + h * 48 + c]; }
;         for (int i = tid; i < 768; i += 512) { const int jj = i / 192, c = i % 192; const int ch = c < 48 ? h * 48 + c : (c < 96 ? 192 + h * 48 + (c - 48) : 384 + h * 96 + (c - 96)); sm[L_CW + i] = cw[jj * 768 + ch]; }
;         if (tid < 48) sm[L_GB + tid] = p.in(27)[l * 192 + h * 48 + tid];
;     }
;     for (int i = tid; i < (L_G15 - L_QG); i += 512) ((LAS unsigned*)(sm + L_QG))[i] = 0u;
.LBB0_198:
	s_or_b64 exec, exec, s[0:1]
	v_readlane_b32 s0, v253, 43
	s_waitcnt lgkmcnt(0)
	s_barrier
	v_cmp_gt_i32_e64 s[10:11], s3, v54
	v_mov_b32_e32 v0, s0
	ds_read_b64 v[2:3], v0
	s_mul_i32 s5, s4, 48
	s_waitcnt lgkmcnt(0)
	v_readfirstlane_b32 s14, v2
	v_readfirstlane_b32 s15, v3
	s_cmpk_gt_u32 s57, 0x5ff
	s_cbranch_scc1 .Lmy_glc_staged
	s_and_saveexec_b64 s[12:13], s[10:11]
	s_cbranch_execz .LBB0_218
	v_readlane_b32 s0, v253, 44
	v_lshlrev_b32_e32 v5, 2, v54
	v_mov_b32_e32 v4, v54
	v_mov_b32_e32 v0, s0
	ds_read_b64 v[2:3], v0
	v_readlane_b32 s0, v253, 45
	v_mov_b32_e32 v0, v54
	s_movk_i32 s2, 0xffd0
	v_add_u32_e32 v6, s0, v5
	s_mov_b64 s[0:1], 0

; #define LAS __attribute__((address_space(3)))
; __device__ __forceinline__ void gl_item_C(const Params& p, int l, int seg, int h, LAS float* sm, int tid, int lane, int wave) {
;     ...
;     for (int i = tid; i < (L_G15 - L_QG); i += 512) ((LAS unsigned*)(sm + L_QG))[i] = 0u;
.Lmy_glc_staged:
	s_movk_i32 s0, 0x1c40
	v_cmp_gt_i32_e32 vcc, s0, v54
	s_and_saveexec_b64 s[0:1], vcc
	s_cbranch_execz .LBB0_223
	s_add_i32 s5, 0, 0x14000
	v_add_u32_e32 v0, 0xfffffe00, v54
	v_lshl_add_u32 v2, v54, 2, s5
	s_mov_b64 s[12:13], 0

; #define LAS __attribute__((address_space(3)))
; __device__ __forceinline__ void gl_item_C(const Params& p, int l, int seg, int h, LAS float* sm, int tid, int lane, int wave) {
;     ...
;         if (wave < 6) {
;             f32x4 o = {0.f, 0.f, 0.f, 0.f};
; #pragma unroll
;             for (int kc = 0; kc < 2; ++kc)
;                 o = __builtin_amdgcn_mfma_f32_16x16x32_bf16(*(const LAS pg8::bf16x8*)(qG + row * QP + 32 * kc + 8 * q), *(const LAS pg8::bf16x8*)(Sb + (16 * wave + row) * SP + 32 * kc + 8 * q), o, 0, 0, 0);
;             const pg8::bf16x8 vb = *(const LAS pg8::bf16x8*)(vT + (16 * wave + row) * TP + 8 * q);
;             o = __builtin_amdgcn_mfma_f32_16x16x32_bf16(*(const LAS pg8::bf16x8*)(Am + row * TP + 8 * q), vb, o, 0, 0, 0);
; #pragma unroll
;             for (int i = 0; i < 4; ++i) ob[(4 * q + i) * 96 + 16 * wave + row] = o[i];
; #pragma unroll
;             for (int m = 0; m < 3; ++m) {
;                 const f32x4 gg = *(const LAS f32x4*)(G15 + 16 * m + 4 * q);
;                 S[m] = __builtin_amdgcn_mfma_f32_16x16x32_bf16(*(const LAS pg8::bf16x8*)(kT + (16 * m + row) * TP + 8 * q), vb, S[m] * gg, 0, 0, 0);
;             }
;         }
.LBB0_345:
	s_or_b64 exec, exec, s[0:1]
	s_waitcnt lgkmcnt(0)
	s_barrier
	s_mul_i32 s0, s4, 0xffffa000
	v_cndmask_b32_e64 v0, 0, 1, s[28:29]
	s_ashr_i32 s35, s34, 31
	s_add_i32 s5, s5, s0
	v_cmp_ne_u32_e64 s[0:1], 1, v0
	s_andn2_b64 vcc, exec, s[28:29]
	s_cbranch_vccnz .LBB0_347
	ds_read_b128 v[50:53], v102
	ds_read_b128 v[58:61], v103
	ds_read_b128 v[208:211], v102 offset:64
	ds_read_b128 v[212:215], v103 offset:64
	ds_read_b128 v[246:249], v104
	s_lshl_b32 s2, s66, 2
	s_add_i32 s2, s5, s2
	v_lshlrev_b32_e32 v0, 2, v55
	v_add3_u32 v0, s2, v0, v123
	v_add_u32_e32 v62, 0xf000, v0
	v_add_u32_e32 v0, 0xf200, v0
	s_waitcnt lgkmcnt(3)
	v_mfma_f32_16x16x32_bf16 v[50:53], v[50:53], v[58:61], 0
	ds_read_b128 v[58:61], v105
	s_waitcnt lgkmcnt(2)
	v_mfma_f32_16x16x32_bf16 v[50:53], v[208:211], v[212:215], v[50:53]
	ds_read_b128 v[208:211], v199
	ds_read_b128 v[212:215], v200
	s_waitcnt lgkmcnt(2)
	v_mfma_f32_16x16x32_bf16 v[50:53], v[58:61], v[246:249], v[50:53]
	ds_read_b128 v[58:61], v199 offset:64
	s_waitcnt lgkmcnt(2)
	v_pk_mul_f32 v[10:11], v[10:11], v[208:209]
	v_pk_mul_f32 v[12:13], v[12:13], v[210:211]
	s_waitcnt lgkmcnt(1)
	s_nop 0
	v_mfma_f32_16x16x32_bf16 v[10:13], v[212:215], v[246:249], v[10:13]
	ds_read_b128 v[208:211], v200 offset:1280
	ds_read_b128 v[212:215], v199 offset:128
	ds_write2_b32 v62, v50, v51 offset1:96
	ds_write2_b32 v0, v52, v53 offset0:64 offset1:160
	ds_read_b128 v[50:53], v200 offset:2560
	s_waitcnt lgkmcnt(5)
	v_pk_mul_f32 v[6:7], v[6:7], v[58:59]
	v_pk_mul_f32 v[8:9], v[8:9], v[60:61]
	s_waitcnt lgkmcnt(4)
	s_nop 0
	v_mfma_f32_16x16x32_bf16 v[6:9], v[208:211], v[246:249], v[6:9]
	s_waitcnt lgkmcnt(3)
	v_pk_mul_f32 v[2:3], v[2:3], v[212:213]
	v_pk_mul_f32 v[4:5], v[4:5], v[214:215]
	s_waitcnt lgkmcnt(0)
	s_nop 0
	v_mfma_f32_16x16x32_bf16 v[2:5], v[50:53], v[246:249], v[2:5]

;     __device__ __forceinline__ const float* in(int i) const { return (const float*)(const __attribute__((address_space(1))) float*)ld(i); }
; template <bool HG>
; __device__ __forceinline__ void diag_item_A(const Params& p, int l, int seg, int h, LAS float* sm, int tid, int lane, int wave) {
;     ...
;     lds_barrier();
;     if (HG) {
;         if (tid < 128) {
;             const float* lg = p.in(23) + h * 128 + tid;
;             const float x0 = lg[0], x1 = lg[512], x2 = lg[1024], x3 = lg[1536];
;             const float m = fmaxf(fmaxf(x0, x1), fmaxf(x2, x3));
;             const float e0 = __expf(x0 - m), e1 = __expf(x1 - m), e2 = __expf(x2 - m), e3 = __expf(x3 - m);
;             const float inv = 1.0f / (e0 + e1 + e2 + e3);
;             float lb = 0.f;
;             if (l >= 1) lb += e1; if (l >= 2) lb += e2; if (l >= 3) lb += e3;
;             sm[L_LB2 + tid] = lb * inv;
;         }
;     } else {
;         const float* cw = p.in(25) + (size_t)l * 4 * 768;
;         for (int i = tid; i < 768; i += 512) { const int r = i / 48, c = i % 48; sm[L_GUP + i] = p.in(26)[(size_t)l * 16 * 192 + r * 192 + h * 48 + c]; }
;         for (int i = tid; i < 768; i += 512) { const int jj = i / 192, c = i % 192; const int ch = c < 48 ? h * 48 + c : (c < 96 ? 192 + h * 48 + (c - 48) : 384 + h * 96 + (c - 96)); sm[L_CW + i] = cw[jj * 768 + ch]; }
;         if (tid < 48) sm[L_GB + tid] = p.in(27)[l * 192 + h * 48 + tid];
; template <int pass>
; __device__ __forceinline__ void phase_scan(const Params& p, int l, LAS unsigned char* lds, int tid, int lane, int wave) {
;     ...
;     for (int it = blockIdx.x; it < N_RW + N_HG + N_GL; it += gridDim.x) {
;         asm volatile("" : "+v"(tid));
;         lane = tid & 63; wave = __builtin_amdgcn_readfirstlane(tid >> 6);
;         if (it < N_RW) rw_item<pass>(p, l, it / 6, it % 6, sm, tid, lane, wave);
;         else if (it < N_RW + N_HG) { if constexpr (pass == 0) diag_item_A<true>(p, l, (it - N_RW) / 4, (it - N_RW) % 4, sm, tid, lane, wave); else hg_item_C(p, l, (it - N_RW) / 4, (it - N_RW) % 4, sm, tid, lane, wave); }
;         else { if constexpr (pass == 0) diag_item_A<false>(p, l, (it - N_RW - N_HG) / 4, (it - N_RW - N_HG) % 4, sm, tid, lane, wave); else gl_item_C(p, l, (it - N_RW - N_HG) / 4, (it - N_RW - N_HG) % 4, sm, tid, lane, wave); }
.LBB0_523:
	v_readlane_b32 s0, v253, 35
	s_cmpk_gt_i32 s18, 0x2ff
	s_waitcnt vmcnt(2)
	v_and_b32_e32 v46, 63, v30
	v_mov_b32_e32 v0, s0
	s_waitcnt lgkmcnt(0)
	ds_read_b64 v[32:33], v0
	v_readfirstlane_b32 s8, v30
	s_mov_b64 s[0:1], -1
	s_cbranch_scc0 .LBB0_722
	s_ashr_i32 s19, s8, 6
	s_and_b32 s30, s18, 3
	s_cmpk_gt_u32 s18, 0x4ff
	s_cbranch_scc0 .LBB0_711
	v_readlane_b32 s0, v253, 43
	s_waitcnt lgkmcnt(0)
	s_barrier
	s_waitcnt lgkmcnt(0)
	v_readfirstlane_b32 s31, v32
	v_mov_b32_e32 v0, s0
	ds_read_b64 v[2:3], v0
	v_readfirstlane_b32 s34, v33
	v_cmp_gt_i32_e64 s[10:11], s3, v30
	s_mul_i32 s22, s30, 48
	s_mul_i32 s24, s30, 0x60
	s_waitcnt lgkmcnt(0)
	v_readfirstlane_b32 s12, v2
	v_readfirstlane_b32 s13, v3
	s_cmpk_gt_u32 s18, 0x5ff
	s_cbranch_scc1 .Lmy_gla_staged
	s_and_saveexec_b64 s[8:9], s[10:11]
	s_cbranch_execz .LBB0_545
	v_readlane_b32 s0, v253, 44
	v_lshlrev_b32_e32 v5, 2, v30
	v_mov_b32_e32 v4, v30
	v_mov_b32_e32 v0, s0
	ds_read_b64 v[2:3], v0
	v_readlane_b32 s0, v253, 45
	v_mov_b32_e32 v0, v30
	s_movk_i32 s2, 0xffd0
	v_add_u32_e32 v6, s0, v5
	s_mov_b64 s[0:1], 0

; #define LAS __attribute__((address_space(3)))
;     __device__ __forceinline__ const float* in(int i) const { return (const float*)(const __attribute__((address_space(1))) float*)ld(i); }
; template <bool HG>
; __device__ __forceinline__ void diag_item_A(const Params& p, int l, int seg, int h, LAS float* sm, int tid, int lane, int wave) {
;     ...
;         for (int i = tid; i < 768; i += 512) { const int r = i / 48, c = i % 48; sm[L_GUP + i] = p.in(26)[(size_t)l * 16 * 192 + r * 192 + h * 48 + c]; }
;         for (int i = tid; i < 768; i += 512) { const int jj = i / 192, c = i % 192; const int ch = c < 48 ? h * 48 + c : (c < 96 ? 192 + h * 48 + (c - 48) : 384 + h * 96 + (c - 96)); sm[L_CW + i] = cw[jj * 768 + ch]; }
;         if (tid < 48) sm[L_GB + tid] = p.in(27)[l * 192 + h * 48 + tid];
;     }
;     for (int i = tid; i < (L_VT - L_KT) + V * TP / 2; i += 512) ((LAS unsigned*)(sm + L_KT))[i] = 0u;
.LBB0_547:
	s_or_b64 exec, exec, s[0:1]
	s_branch .Lmy_gla_cont
.Lmy_gla_staged:
	v_cmp_gt_i32_e64 s[8:9], 48, v30
.Lmy_gla_cont:
	s_movk_i32 s0, 0x1180
	v_cmp_gt_i32_e32 vcc, s0, v30
	s_and_saveexec_b64 s[0:1], vcc
	s_cbranch_execz .LBB0_550
	s_add_i32 s12, 0, 0x14000
	v_add_u32_e32 v0, 0xfffffe00, v30
	v_lshl_add_u32 v2, v30, 2, s12
	s_mov_b64 s[12:13], 0

; #define LAS __attribute__((address_space(3)))
; __device__ __forceinline__ bf16_t f2bf(float f) { unsigned u = __float_as_uint(f); u += 0x7FFFu + ((u >> 16) & 1u); return (bf16_t)(u >> 16); }
; __device__ __forceinline__ void lds_barrier() { asm volatile("s_waitcnt lgkmcnt(0)" ::: "memory"); __builtin_amdgcn_s_barrier(); asm volatile("" ::: "memory"); }
; template <bool HG>
; __device__ __forceinline__ void diag_item_A(const Params& p, int l, int seg, int h, LAS float* sm, int tid, int lane, int wave) {
;     ...
;         { float vv_[EV];
; #pragma unroll
;           for (int e = 0; e < EV; ++e) vv_[e] = bf[6144 + tid + 512 * e];
; #pragma unroll
;           for (int e = 0; e < EV; ++e) { const int idx = tid + 512 * e; vT[(idx % V) * TP + (idx / V)] = f2bf(vv_[e]); } }
;         lds_barrier();
;         if (HG) {
;             const pg8::bf16x8 a = *(const LAS pg8::bf16x8*)(kT + (16 * wave + row) * TP + 8 * q);
; #pragma unroll
;             for (int n = 0; n < 4; ++n) acc[n] = __builtin_amdgcn_mfma_f32_16x16x32_bf16(a, *(const LAS pg8::bf16x8*)(vT + (16 * n + row) * TP + 8 * q), acc[n], 0, 0, 0);
;         } else if (wave < 6) {
;             const pg8::bf16x8 b = *(const LAS pg8::bf16x8*)(vT + (16 * wave + row) * TP + 8 * q);
; #pragma unroll
;             for (int m = 0; m < 3; ++m) acc[m] = __builtin_amdgcn_mfma_f32_16x16x32_bf16(*(const LAS pg8::bf16x8*)(kT + (16 * m + row) * TP + 8 * q), b, acc[m], 0, 0, 0);
;         }
.LBB0_646:
	s_or_b64 exec, exec, s[0:1]
	ds_read2st64_b32 v[140:141], v139 offset0:96 offset1:104
	ds_read_b32 v34, v139 offset:28672
	s_andn2_b64 vcc, exec, s[22:23]
	s_waitcnt lgkmcnt(1)
	v_bfe_u32 v139, v140, 16, 1
	v_add3_u32 v139, v140, v139, s61
	ds_write_b16_d16_hi v71, v139
	v_bfe_u32 v139, v141, 16, 1
	v_add3_u32 v139, v141, v139, s61
	ds_write_b16_d16_hi v69, v139
	s_waitcnt lgkmcnt(2)
	v_bfe_u32 v139, v34, 16, 1
	v_add3_u32 v34, v34, v139, s61
	ds_write_b16_d16_hi v70, v34
	s_waitcnt lgkmcnt(0)
	s_barrier
	v_cndmask_b32_e64 v34, 0, 1, s[22:23]
	v_cmp_ne_u32_e64 s[14:15], 1, v34
	s_cbranch_vccnz .LBB0_648
	v_add_u32_e32 v34, v127, v128
	ds_read_b128 v[140:143], v68
	ds_read_b128 v[144:147], v34
	ds_read_b128 v[204:207], v34 offset:1280
	ds_read_b128 v[208:211], v34 offset:2560
	s_waitcnt lgkmcnt(2)
	v_mfma_f32_16x16x32_bf16 v[18:21], v[144:147], v[140:143], v[18:21]
	s_waitcnt lgkmcnt(1)
	v_mfma_f32_16x16x32_bf16 v[26:29], v[204:207], v[140:143], v[26:29]
	s_waitcnt lgkmcnt(0)
	v_mfma_f32_16x16x32_bf16 v[22:25], v[208:211], v[140:143], v[22:25]

; #define LAS __attribute__((address_space(3)))
; __device__ __forceinline__ bf16_t f2bf(float f) { unsigned u = __float_as_uint(f); u += 0x7FFFu + ((u >> 16) & 1u); return (bf16_t)(u >> 16); }
; __device__ __forceinline__ void lds_barrier() { asm volatile("s_waitcnt lgkmcnt(0)" ::: "memory"); __builtin_amdgcn_s_barrier(); asm volatile("" ::: "memory"); }
; template <bool HG>
; __device__ __forceinline__ void diag_item_A(const Params& p, int l, int seg, int h, LAS float* sm, int tid, int lane, int wave) {
;     ...
;         { float vv_[EV];
; #pragma unroll
;           for (int e = 0; e < EV; ++e) vv_[e] = bf[6144 + tid + 512 * e];
; #pragma unroll
;           for (int e = 0; e < EV; ++e) { const int idx = tid + 512 * e; vT[(idx % V) * TP + (idx / V)] = f2bf(vv_[e]); } }
;         lds_barrier();
;         if (HG) {
;             const pg8::bf16x8 a = *(const LAS pg8::bf16x8*)(kT + (16 * wave + row) * TP + 8 * q);
; #pragma unroll
;             for (int n = 0; n < 4; ++n) acc[n] = __builtin_amdgcn_mfma_f32_16x16x32_bf16(a, *(const LAS pg8::bf16x8*)(vT + (16 * n + row) * TP + 8 * q), acc[n], 0, 0, 0);
;         } else if (wave < 6) {
;             const pg8::bf16x8 b = *(const LAS pg8::bf16x8*)(vT + (16 * wave + row) * TP + 8 * q);
; #pragma unroll
;             for (int m = 0; m < 3; ++m) acc[m] = __builtin_amdgcn_mfma_f32_16x16x32_bf16(*(const LAS pg8::bf16x8*)(kT + (16 * m + row) * TP + 8 * q), b, acc[m], 0, 0, 0);
;         }
.LBB0_704:
	s_or_b64 exec, exec, s[0:1]
	ds_read2st64_b32 v[2:3], v53 offset0:96 offset1:104
	ds_read_b32 v0, v53 offset:28672
	s_and_b64 vcc, exec, s[14:15]
	s_waitcnt lgkmcnt(1)
	v_bfe_u32 v4, v2, 16, 1
	v_add3_u32 v2, v2, v4, s61
	ds_write_b16_d16_hi v71, v2
	v_bfe_u32 v2, v3, 16, 1
	v_add3_u32 v2, v3, v2, s61
	ds_write_b16_d16_hi v69, v2
	s_waitcnt lgkmcnt(2)
	v_bfe_u32 v2, v0, 16, 1
	v_add3_u32 v0, v0, v2, s61
	ds_write_b16_d16_hi v70, v0
	s_waitcnt lgkmcnt(0)
	s_barrier
	s_cbranch_vccnz .LBB0_706
	ds_read_b128 v[2:5], v68
	ds_read_b128 v[6:9], v37
	ds_read_b128 v[204:207], v37 offset:1280
	ds_read_b128 v[208:211], v37 offset:2560
	s_waitcnt lgkmcnt(2)
	v_mfma_f32_16x16x32_bf16 v[18:21], v[6:9], v[2:5], v[18:21]
	s_waitcnt lgkmcnt(1)
	v_mfma_f32_16x16x32_bf16 v[26:29], v[204:207], v[2:5], v[26:29]
	s_waitcnt lgkmcnt(0)
	v_mfma_f32_16x16x32_bf16 v[22:25], v[208:211], v[2:5], v[22:25]

; #define LAS __attribute__((address_space(3)))
; __device__ __forceinline__ bf16_t f2bf(float f) { unsigned u = __float_as_uint(f); u += 0x7FFFu + ((u >> 16) & 1u); return (bf16_t)(u >> 16); }
; __device__ __forceinline__ void lds_barrier() { asm volatile("s_waitcnt lgkmcnt(0)" ::: "memory"); __builtin_amdgcn_s_barrier(); asm volatile("" ::: "memory"); }
; template <bool HG>
; __device__ __forceinline__ void diag_item_A(const Params& p, int l, int seg, int h, LAS float* sm, int tid, int lane, int wave) {
;     ...
;         if (tid < K) {
;             float dd[TS], kk_[TS];
; #pragma unroll
;             for (int t = 0; t < TS; ++t) { dd[t] = bf[2048 + t * K + tid]; kk_[t] = bf[4096 + t * K + tid]; }
; #pragma unroll
;             for (int t = TS - 1; t >= 0; --t) { kT[tid * TP + t] = f2bf(kk_[t] * R); R *= dd[t]; }
;         }
;         { float vv_[EV];
; #pragma unroll
;           for (int e = 0; e < EV; ++e) vv_[e] = bf[6144 + tid + 512 * e];
; #pragma unroll
;           for (int e = 0; e < EV; ++e) { const int idx = tid + 512 * e; vT[(idx % V) * TP + (idx / V)] = f2bf(vv_[e]); } }
;         lds_barrier();
;         if (HG) {
;             const pg8::bf16x8 a = *(const LAS pg8::bf16x8*)(kT + (16 * wave + row) * TP + 8 * q);
; #pragma unroll
;             for (int n = 0; n < 4; ++n) acc[n] = __builtin_amdgcn_mfma_f32_16x16x32_bf16(a, *(const LAS pg8::bf16x8*)(vT + (16 * n + row) * TP + 8 * q), acc[n], 0, 0, 0);
;         } else if (wave < 6) {
;             const pg8::bf16x8 b = *(const LAS pg8::bf16x8*)(vT + (16 * wave + row) * TP + 8 * q);
; #pragma unroll
;             for (int m = 0; m < 3; ++m) acc[m] = __builtin_amdgcn_mfma_f32_16x16x32_bf16(*(const LAS pg8::bf16x8*)(kT + (16 * m + row) * TP + 8 * q), b, acc[m], 0, 0, 0);
;         }
;         if (sbi + 1 < SEG / TS) DG_STORE(cur ^ 1);
;         if (sbi + 2 < SEG / TS) DG_LOAD(sb - 2);
;         lds_barrier();
.LBB0_733:
	s_or_b64 exec, exec, s[10:11]
	ds_read2st64_b32 v[18:19], v24 offset0:216 offset1:224
	s_waitcnt lgkmcnt(0)
	v_bfe_u32 v20, v18, 16, 1
	v_add3_u32 v18, v18, v20, s61
	ds_write_b16_d16_hi v29, v18
	v_bfe_u32 v18, v19, 16, 1
	v_add3_u32 v18, v19, v18, s61
	ds_write_b16_d16_hi v28, v18
	s_waitcnt lgkmcnt(0)
	s_barrier
	ds_read_b128 v[38:41], v27
	ds_read_b128 v[18:21], v34
	ds_read_b128 v[204:207], v34 offset:1280
	ds_read_b128 v[208:211], v34 offset:2560
	ds_read_b128 v[212:215], v0
	s_waitcnt lgkmcnt(3)
	v_mfma_f32_16x16x32_bf16 v[18:21], v[38:41], v[18:21], v[6:9]
	s_waitcnt lgkmcnt(2)
	v_mfma_f32_16x16x32_bf16 v[10:13], v[38:41], v[204:207], v[10:13]
	s_waitcnt lgkmcnt(1)
	v_mfma_f32_16x16x32_bf16 v[6:9], v[38:41], v[208:211], v[14:17]
	s_waitcnt lgkmcnt(0)
	v_mfma_f32_16x16x32_bf16 v[2:5], v[38:41], v[212:215], v[2:5]
	s_nop 1
	s_waitcnt vmcnt(0)
	v_lshlrev_b32_e32 v14, 16, v246
	v_mul_f32_e32 v14, 0xbfb8aa3b, v14
	v_exp_f32_e32 v14, v14
	ds_read_b32 v15, v35
	v_add_f32_e32 v14, 1.0, v14
	v_rcp_f32_e32 v14, v14
	s_waitcnt lgkmcnt(0)
	v_sub_f32_e32 v16, 1.0, v15
	v_fmac_f32_e32 v15, v14, v16
	v_sub_f32_e32 v14, 1.0, v14
	v_mul_f32_e32 v14, v14, v16
	ds_write_b32 v24, v14 offset:16384
	v_lshlrev_b32_e32 v14, 16, v247
	v_mul_f32_e32 v14, 0xbfb8aa3b, v14
	v_exp_f32_e32 v14, v14
	v_max_f32_e32 v15, 0xda24260, v15
	ds_write_b32 v24, v15 offset:8192
	ds_read_b32 v15, v35
	v_add_f32_e32 v14, 1.0, v14
	v_rcp_f32_e32 v14, v14
	s_waitcnt lgkmcnt(0)
	v_sub_f32_e32 v16, 1.0, v15
	v_fmac_f32_e32 v15, v14, v16
	v_sub_f32_e32 v14, 1.0, v14
	v_mul_f32_e32 v14, v14, v16
	ds_write_b32 v24, v14 offset:18432
	v_lshlrev_b32_e32 v14, 16, v248
	v_mul_f32_e32 v14, 0xbfb8aa3b, v14
	v_exp_f32_e32 v14, v14
	v_max_f32_e32 v15, 0xda24260, v15
	ds_write_b32 v24, v15 offset:10240
	ds_read_b32 v15, v35
	v_add_f32_e32 v14, 1.0, v14
	v_rcp_f32_e32 v14, v14
	s_waitcnt lgkmcnt(0)
	v_sub_f32_e32 v16, 1.0, v15
	v_fmac_f32_e32 v15, v14, v16
	v_sub_f32_e32 v14, 1.0, v14
	v_mul_f32_e32 v14, v14, v16
	ds_write_b32 v24, v14 offset:20480
	v_lshlrev_b32_e32 v14, 16, v249
	v_mul_f32_e32 v14, 0xbfb8aa3b, v14
	v_exp_f32_e32 v14, v14
	v_max_f32_e32 v15, 0xda24260, v15
	ds_write_b32 v24, v15 offset:12288
	ds_read_b32 v15, v35
	v_add_f32_e32 v14, 1.0, v14
	v_rcp_f32_e32 v14, v14
	s_waitcnt lgkmcnt(0)
	v_sub_f32_e32 v16, 1.0, v15
	v_fmac_f32_e32 v15, v14, v16
	v_max_f32_e32 v15, 0xda24260, v15
	v_sub_f32_e32 v14, 1.0, v14
	ds_write_b32 v24, v15 offset:14336
	v_mul_f32_e32 v14, v14, v16
	v_lshlrev_b32_e32 v15, 16, v250
	ds_write2st64_b32 v24, v14, v15 offset0:88 offset1:96
	v_lshlrev_b32_e32 v14, 16, v251
	ds_write_b32 v24, v14 offset:26624
	s_waitcnt lgkmcnt(0)
	s_barrier
	s_and_saveexec_b64 s[10:11], s[8:9]
	s_cbranch_execz .LBB0_735
	ds_read2st64_b32 v[38:39], v24 offset0:32 offset1:34
	ds_read2st64_b32 v[40:41], v24 offset0:64 offset1:66
	ds_read2st64_b32 v[42:43], v24 offset0:36 offset1:38
	ds_read2st64_b32 v[44:45], v24 offset0:68 offset1:70
	ds_read2st64_b32 v[48:49], v24 offset0:40 offset1:42
	ds_read2st64_b32 v[50:51], v24 offset0:72 offset1:74
	ds_read2st64_b32 v[52:53], v24 offset0:44 offset1:46
	ds_read2st64_b32 v[54:55], v24 offset0:76 offset1:78
	ds_read2st64_b32 v[56:57], v24 offset0:48 offset1:50
	ds_read2st64_b32 v[14:15], v24 offset0:80 offset1:82
	ds_read2st64_b32 v[16:17], v24 offset0:52 offset1:54
	ds_read2st64_b32 v[58:59], v24 offset0:60 offset1:62
	ds_read2st64_b32 v[60:61], v24 offset0:84 offset1:86
	ds_read2st64_b32 v[62:63], v24 offset0:56 offset1:58
	ds_read2st64_b32 v[64:65], v24 offset0:88 offset1:90
	ds_read2st64_b32 v[66:67], v24 offset0:92 offset1:94
	s_waitcnt lgkmcnt(4)
	v_mul_f32_e32 v22, v23, v59
	v_mul_f32_e32 v59, v58, v22
	s_waitcnt lgkmcnt(2)
	v_mul_f32_e32 v58, v63, v59
	s_waitcnt lgkmcnt(1)
	v_pk_mul_f32 v[64:65], v[58:59], v[64:65]
	s_waitcnt lgkmcnt(0)
	v_pk_mul_f32 v[22:23], v[22:23], v[66:67]
	v_bfe_u32 v59, v64, 16, 1
	v_bfe_u32 v35, v23, 16, 1
	v_bfe_u32 v37, v22, 16, 1
	v_add3_u32 v35, v23, v35, s61
	v_mul_f32_e32 v23, v62, v58
	v_add3_u32 v37, v22, v37, s61
	v_mul_f32_e32 v22, v17, v23
	v_add3_u32 v63, v64, v59, s61
	v_mul_f32_e32 v59, v16, v22
	v_mul_f32_e32 v58, v57, v59
	v_pk_mul_f32 v[14:15], v[14:15], v[58:59]
	v_pk_mul_f32 v[16:17], v[60:61], v[22:23]
	v_bfe_u32 v47, v65, 16, 1
	v_bfe_u32 v22, v17, 16, 1
	v_bfe_u32 v23, v16, 16, 1
	v_bfe_u32 v57, v15, 16, 1
	v_bfe_u32 v59, v14, 16, 1
	v_add3_u32 v47, v65, v47, s61
	v_add3_u32 v14, v14, v59, s61
	v_add3_u32 v57, v15, v57, s61
	v_add3_u32 v15, v16, v23, s61
	v_add3_u32 v22, v17, v22, s61
	v_perm_b32 v17, v35, v37, s46
	v_perm_b32 v16, v47, v63, s46
	v_perm_b32 v15, v22, v15, s46
	v_perm_b32 v14, v57, v14, s46
	ds_write_b128 v36, v[14:17] offset:16
	v_mul_f32_e32 v15, v56, v58
	v_mul_f32_e32 v14, v53, v15
	v_mul_f32_e32 v17, v52, v14
	v_mul_f32_e32 v16, v49, v17
	v_pk_mul_f32 v[14:15], v[54:55], v[14:15]
	v_pk_mul_f32 v[22:23], v[50:51], v[16:17]
	v_bfe_u32 v17, v15, 16, 1
	v_bfe_u32 v35, v14, 16, 1
	v_add3_u32 v49, v15, v17, s61
	v_mul_f32_e32 v15, v48, v16
	v_bfe_u32 v37, v23, 16, 1
	v_add3_u32 v35, v14, v35, s61
	v_mul_f32_e32 v14, v43, v15
	v_bfe_u32 v47, v22, 16, 1
	v_add3_u32 v37, v23, v37, s61
	v_mul_f32_e32 v23, v42, v14
	v_add3_u32 v47, v22, v47, s61
	v_mul_f32_e32 v22, v39, v23
	v_pk_mul_f32 v[16:17], v[40:41], v[22:23]
	v_pk_mul_f32 v[14:15], v[44:45], v[14:15]
	v_bfe_u32 v40, v17, 16, 1
	v_bfe_u32 v23, v15, 16, 1
	v_bfe_u32 v39, v14, 16, 1
	v_bfe_u32 v41, v16, 16, 1
	v_add3_u32 v41, v16, v41, s61
	v_add3_u32 v40, v17, v40, s61
	v_add3_u32 v14, v14, v39, s61
	v_add3_u32 v15, v15, v23, s61
	v_perm_b32 v17, v49, v35, s46
	v_perm_b32 v16, v37, v47, s46
	v_perm_b32 v15, v15, v14, s46
	v_perm_b32 v14, v40, v41, s46
	v_mul_f32_e32 v23, v38, v22
	ds_write_b128 v36, v[14:17]

; #define LAS __attribute__((address_space(3)))
; template <bool HG>
; __device__ __forceinline__ void diag_item_A(const Params& p, int l, int seg, int h, LAS float* sm, int tid, int lane, int wave) {
;     ...
;         } else if (wave < 6) {
;             const pg8::bf16x8 b = *(const LAS pg8::bf16x8*)(vT + (16 * wave + row) * TP + 8 * q);
; #pragma unroll
;             for (int m = 0; m < 3; ++m) acc[m] = __builtin_amdgcn_mfma_f32_16x16x32_bf16(*(const LAS pg8::bf16x8*)(kT + (16 * m + row) * TP + 8 * q), b, acc[m], 0, 0, 0);
;         }
;         if (sbi + 1 < SEG / TS) DG_STORE(cur ^ 1);
.LBB0_738:
	ds_read_b128 v[38:41], v68
	ds_read_b128 v[42:45], v37
	ds_read_b128 v[204:207], v37 offset:1280
	ds_read_b128 v[208:211], v37 offset:2560
	s_waitcnt lgkmcnt(2)
	v_mfma_f32_16x16x32_bf16 v[18:21], v[42:45], v[38:41], v[18:21]
	s_waitcnt lgkmcnt(1)
	v_mfma_f32_16x16x32_bf16 v[26:29], v[204:207], v[38:41], v[26:29]
	s_waitcnt lgkmcnt(0)
	v_mfma_f32_16x16x32_bf16 v[22:25], v[208:211], v[38:41], v[22:25]
	s_and_saveexec_b64 s[20:21], s[10:11]
	s_cbranch_execz .LBB0_700
